# hgrn pass2 start-state loop: all 16 loads of a segment issued before the first wait (was 8 serial round trips per earlier segment)
# speedup vs baseline: 1.0153x; 1.0046x over previous
; template <bool FULL>
; __device__ __forceinline__ void hgrn_seg(CArgs& a, LAS unsigned char* lds, int layer, int item, const bf16* z, bf16* mix, float* HS, float* HD) {
;     ...
;     if (FULL) {
;         for (int j = 0; j < sgi; ++j) { const float* Sj = HS + (size_t)(item - sgi + j) * 16384 + (16 * wave + fr) * 128 + 4 * fq; const float* Dj = HD + (item - sgi + j) * 128 + 4 * fq;
; #pragma unroll
;             for (int kb = 0; kb < 8; ++kb) st[kb] = st[kb] * *(const f32x4*)(Dj + 16 * kb) + *(const f32x4*)(Sj + 16 * kb); }
.LBB0_121:
	v_lshl_add_u64 v[44:45], s[10:11], 0, v[0:1]
	s_mov_b32 s16, 0x1b500000
	v_add_co_u32_e32 v54, vcc, s16, v44
	v_lshl_add_u64 v[52:53], v[2:3], 0, v[0:1]
	s_nop 0
	v_addc_co_u32_e32 v55, vcc, 0, v45, vcc
	global_load_dwordx4 v[180:183], v[54:55], off
	global_load_dwordx4 v[184:187], v[52:53], off offset:-256
	global_load_dwordx4 v[188:191], v[54:55], off offset:64
	global_load_dwordx4 v[192:195], v[52:53], off offset:-192
	global_load_dwordx4 v[196:199], v[54:55], off offset:128
	global_load_dwordx4 v[200:203], v[52:53], off offset:-128
	global_load_dwordx4 v[204:207], v[54:55], off offset:192
	global_load_dwordx4 v[208:211], v[52:53], off offset:-64
	global_load_dwordx4 v[212:215], v[54:55], off offset:256
	global_load_dwordx4 v[216:219], v[52:53], off
	global_load_dwordx4 v[220:223], v[54:55], off offset:320
	global_load_dwordx4 v[224:227], v[52:53], off offset:64
	global_load_dwordx4 v[228:231], v[54:55], off offset:384
	global_load_dwordx4 v[232:235], v[52:53], off offset:128
	global_load_dwordx4 v[236:239], v[54:55], off offset:448
	global_load_dwordx4 v[240:243], v[52:53], off offset:192
	s_add_i32 s15, s15, -1
	s_add_u32 s10, s10, 0x200
	s_addc_u32 s11, s11, 0
	s_mov_b64 s[16:17], 0x10000
	v_lshl_add_u64 v[2:3], v[2:3], 0, s[16:17]
	s_cmp_eq_u32 s15, 0
	s_waitcnt vmcnt(14)
	v_pk_fma_f32 v[34:35], v[34:35], v[182:183], v[186:187]
	v_pk_fma_f32 v[32:33], v[32:33], v[180:181], v[184:185]
	s_waitcnt vmcnt(12)
	v_pk_fma_f32 v[6:7], v[6:7], v[190:191], v[194:195]
	v_pk_fma_f32 v[4:5], v[4:5], v[188:189], v[192:193]
	s_waitcnt vmcnt(10)
	v_pk_fma_f32 v[10:11], v[10:11], v[198:199], v[202:203]
	v_pk_fma_f32 v[8:9], v[8:9], v[196:197], v[200:201]
	s_waitcnt vmcnt(8)
	v_pk_fma_f32 v[14:15], v[14:15], v[206:207], v[210:211]
	v_pk_fma_f32 v[12:13], v[12:13], v[204:205], v[208:209]
	s_waitcnt vmcnt(6)
	v_pk_fma_f32 v[18:19], v[18:19], v[214:215], v[218:219]
	v_pk_fma_f32 v[16:17], v[16:17], v[212:213], v[216:217]
	s_waitcnt vmcnt(4)
	v_pk_fma_f32 v[22:23], v[22:23], v[222:223], v[226:227]
	v_pk_fma_f32 v[20:21], v[20:21], v[220:221], v[224:225]
	s_waitcnt vmcnt(2)
	v_pk_fma_f32 v[26:27], v[26:27], v[230:231], v[234:235]
	v_pk_fma_f32 v[24:25], v[24:25], v[228:229], v[232:233]
	s_waitcnt vmcnt(0)
	v_pk_fma_f32 v[30:31], v[30:31], v[238:239], v[242:243]
	v_pk_fma_f32 v[28:29], v[28:29], v[236:237], v[240:241]
	s_cbranch_scc0 .LBB0_121
	s_mov_b32 s76, s80
	s_branch .LBB0_124
